# P6 sample-row LRU-gate skinny GEMM moved to workgroups 0..63; P4 sample-panel units skip the MFMA bursts of the all-padding row half
# speedup vs baseline: 1.0356x; 1.0021x over previous
; #define PG8_STAGE(bufoff, gbase, voff) do { _Pragma("unroll") for (int _i = 0; _i < 2; ++_i) \
;         __builtin_amdgcn_global_load_lds((const unsigned*)((const char*)(gbase) + (voff)[_i]), (LAS unsigned*)(lds + (bufoff) + ldsw + _i * 8192), 16, 0, 0); } while (0)
; #define PG8_LDA(dst, b, h) do { _Pragma("unroll") for (int m = 0; m < 4; ++m) _Pragma("unroll") for (int k = 0; k < 2; ++k) dst[m][k] = *(const LAS bf16x8*)(lds + PG8_SA(b, h) + aoff + m * 2048 + k * 1024); } while (0)
; #define PG8_LDB(dst, b, h) do { _Pragma("unroll") for (int n = 0; n < 2; ++n) _Pragma("unroll") for (int k = 0; k < 2; ++k) dst[n][k] = *(const LAS bf16x8*)(lds + PG8_SB(b, h) + boff + n * 2048 + k * 1024); } while (0)
; #define PG8_MMA(ai, bj, At, Bt) do { __builtin_amdgcn_s_setprio(1); _Pragma("unroll") for (int m = 0; m < 4; ++m) _Pragma("unroll") for (int n = 0; n < 2; ++n) _Pragma("unroll") for (int k = 0; k < 2; ++k) \
;         acc[ai][bj][m][n] = __builtin_amdgcn_mfma_f32_16x16x32_bf16(Bt[n][k], At[m][k], acc[ai][bj][m][n], 0, 0, 0); __builtin_amdgcn_s_setprio(0); } while (0)
; #define PG8_WAIT_V(n) asm volatile("s_waitcnt vmcnt(" #n ")" ::: "memory")
; #define PG8_BAR __builtin_amdgcn_s_barrier()
; template <class Epi>
; __device__ __forceinline__ void gemm_phase(LAS unsigned char* lds, const Gemm g, const Sched& S, const Epi& E) {
;     ...
;             PG8_LDB(B0, 0, 0); PG8_LDB(B1, 0, 1); PG8_SCHED; PG8_LDA(At, 0, 0); PG8_STAGE(PG8_SA(1, 1), a1 + hstepA, voffA);
;             PG8_WAIT_V(8); PG8_WAIT_L(0); PG8_BAR; PG8_MMA(0, 0, At, B0); PG8_MMA(0, 1, At, B1); PG8_BAR; PG8_SCHED;
;             PG8_LDA(At, 0, 1); PG8_STAGE(PG8_SB(0, 0), b2, voffB); PG8_STAGE(PG8_SB(0, 1), b2 + hstepB, voffB); PG8_STAGE(PG8_SA(0, 0), a2, voffA);
;             PG8_WAIT_V(8); PG8_WAIT_L(0); PG8_BAR; PG8_MMA(1, 0, At, B0); PG8_MMA(1, 1, At, B1); PG8_BAR; PG8_SCHED;
;             PG8_LDB(B0, 1, 0); PG8_LDB(B1, 1, 1); PG8_SCHED; PG8_LDA(At, 1, 0); PG8_STAGE(PG8_SA(0, 1), a2 + hstepA, voffA);
;             PG8_WAIT_V(8); PG8_WAIT_L(0); PG8_BAR; PG8_MMA(0, 0, At, B0); PG8_MMA(0, 1, At, B1); PG8_BAR; PG8_SCHED;
;             PG8_LDA(At, 1, 1); PG8_STAGE(PG8_SB(1, 0), b3, voffB); PG8_STAGE(PG8_SB(1, 1), b3 + hstepB, voffB); PG8_STAGE(PG8_SA(1, 0), a3, voffA);
;             PG8_WAIT_V(8); PG8_WAIT_L(0); PG8_BAR; PG8_MMA(1, 0, At, B0); PG8_MMA(1, 1, At, B1); PG8_BAR; PG8_SCHED;
.LBB0_520:
	ds_read_b128 v[128:131], v160
	ds_read_b128 v[132:135], v160 offset:1024
	ds_read_b128 v[152:155], v160 offset:2048
	ds_read_b128 v[164:167], v160 offset:3072
	ds_read_b128 v[168:171], v161
	ds_read_b128 v[172:175], v161 offset:1024
	ds_read_b128 v[176:179], v161 offset:2048
	ds_read_b128 v[180:183], v161 offset:3072
	s_add_u32 s4, s2, 0xfffc0080
	s_addc_u32 s5, s3, -1
	s_cmp_eq_u32 s57, 12
	s_cselect_b32 s53, s0, s5
	s_cselect_b32 s52, s27, s4
	s_cselect_b32 s5, s25, s56
	s_cselect_b32 s4, s54, s55
	v_lshl_add_u64 v[200:201], s[2:3], 0, v[146:147]
	s_add_i32 m0, s10, 0xc000
	ds_read_b128 v[184:187], v162
	ds_read_b128 v[188:191], v162 offset:1024
	ds_read_b128 v[192:195], v162 offset:2048
	ds_read_b128 v[196:199], v162 offset:3072
	ds_read_b128 v[204:207], v162 offset:4096
	ds_read_b128 v[208:211], v162 offset:5120
	ds_read_b128 v[212:215], v162 offset:6144
	ds_read_b128 v[216:219], v162 offset:7168
	global_load_lds_dwordx4 v[200:201], off
	v_lshl_add_u64 v[200:201], s[2:3], 0, v[148:149]
	s_add_i32 m0, s10, 0xe000
	s_nop 0
	global_load_lds_dwordx4 v[200:201], off
	s_waitcnt vmcnt(8)
	s_waitcnt lgkmcnt(0)
	s_barrier
	s_setprio 1
	s_waitcnt lgkmcnt(0)
	v_mfma_f32_16x16x32_bf16 v[124:127], v[128:131], v[184:187], v[124:127]
	v_mfma_f32_16x16x32_bf16 v[116:119], v[152:155], v[184:187], v[116:119]
	v_mfma_f32_16x16x32_bf16 v[108:111], v[128:131], v[192:195], v[108:111]
	v_mfma_f32_16x16x32_bf16 v[100:103], v[152:155], v[192:195], v[100:103]
	v_mfma_f32_16x16x32_bf16 v[92:95], v[128:131], v[204:207], v[92:95]
	v_mfma_f32_16x16x32_bf16 v[84:87], v[152:155], v[204:207], v[84:87]
	v_mfma_f32_16x16x32_bf16 v[76:79], v[128:131], v[212:215], v[76:79]
	v_mfma_f32_16x16x32_bf16 v[68:71], v[152:155], v[212:215], v[68:71]
	v_mfma_f32_16x16x32_bf16 v[124:127], v[132:135], v[188:191], v[124:127]
	v_mfma_f32_16x16x32_bf16 v[116:119], v[164:167], v[188:191], v[116:119]
	v_mfma_f32_16x16x32_bf16 v[108:111], v[132:135], v[196:199], v[108:111]
	v_mfma_f32_16x16x32_bf16 v[100:103], v[164:167], v[196:199], v[100:103]
	v_mfma_f32_16x16x32_bf16 v[92:95], v[132:135], v[208:211], v[92:95]
	v_mfma_f32_16x16x32_bf16 v[84:87], v[164:167], v[208:211], v[84:87]
	v_mfma_f32_16x16x32_bf16 v[76:79], v[132:135], v[216:219], v[76:79]
	v_mfma_f32_16x16x32_bf16 v[68:71], v[164:167], v[216:219], v[68:71]
	v_mfma_f32_16x16x32_bf16 v[120:123], v[168:171], v[184:187], v[120:123]
	v_mfma_f32_16x16x32_bf16 v[112:115], v[176:179], v[184:187], v[112:115]
	v_mfma_f32_16x16x32_bf16 v[104:107], v[168:171], v[192:195], v[104:107]
	v_mfma_f32_16x16x32_bf16 v[96:99], v[176:179], v[192:195], v[96:99]
	v_mfma_f32_16x16x32_bf16 v[88:91], v[168:171], v[204:207], v[88:91]
	v_mfma_f32_16x16x32_bf16 v[80:83], v[176:179], v[204:207], v[80:83]
	v_mfma_f32_16x16x32_bf16 v[72:75], v[168:171], v[212:215], v[72:75]
	v_mfma_f32_16x16x32_bf16 v[64:67], v[176:179], v[212:215], v[64:67]
	v_mfma_f32_16x16x32_bf16 v[120:123], v[172:175], v[188:191], v[120:123]
	v_mfma_f32_16x16x32_bf16 v[112:115], v[180:183], v[188:191], v[112:115]
	v_mfma_f32_16x16x32_bf16 v[104:107], v[172:175], v[196:199], v[104:107]
	v_mfma_f32_16x16x32_bf16 v[96:99], v[180:183], v[196:199], v[96:99]
	v_mfma_f32_16x16x32_bf16 v[88:91], v[172:175], v[208:211], v[88:91]
	v_mfma_f32_16x16x32_bf16 v[80:83], v[180:183], v[208:211], v[80:83]
	v_mfma_f32_16x16x32_bf16 v[72:75], v[172:175], v[216:219], v[72:75]
	v_mfma_f32_16x16x32_bf16 v[64:67], v[180:183], v[216:219], v[64:67]
	s_setprio 0
	s_barrier
	s_add_i32 s58, s89, s86
	v_lshl_add_u64 v[200:201], s[4:5], 0, v[138:139]
	s_mov_b32 m0, s58
	ds_read_b128 v[184:187], v162 offset:16384
	ds_read_b128 v[188:191], v162 offset:17408
	ds_read_b128 v[192:195], v162 offset:18432
	ds_read_b128 v[196:199], v162 offset:19456
	ds_read_b128 v[204:207], v162 offset:20480
	ds_read_b128 v[208:211], v162 offset:21504
	ds_read_b128 v[212:215], v162 offset:22528
	ds_read_b128 v[216:219], v162 offset:23552
	global_load_lds_dwordx4 v[200:201], off
	s_add_i32 m0, s58, 0x2000
	s_add_u32 s58, s4, 0x40000
	v_lshl_add_u64 v[220:221], s[4:5], 0, v[142:143]
	s_addc_u32 s59, s5, 0
	s_add_i32 s60, s90, s86
	global_load_lds_dwordx4 v[220:221], off
	v_lshl_add_u64 v[222:223], s[58:59], 0, v[138:139]
	s_mov_b32 m0, s60
	v_lshl_add_u64 v[224:225], s[52:53], 0, v[140:141]
	global_load_lds_dwordx4 v[222:223], off
	v_lshl_add_u64 v[222:223], s[58:59], 0, v[142:143]
	s_add_i32 m0, s60, 0x2000
	s_nop 0
	global_load_lds_dwordx4 v[222:223], off
	v_lshl_add_u64 v[222:223], s[52:53], 0, v[136:137]
	s_mov_b32 m0, s10
	s_nop 0
	global_load_lds_dwordx4 v[222:223], off
	s_mov_b32 m0, s11
	s_nop 0
	global_load_lds_dwordx4 v[224:225], off
	s_waitcnt vmcnt(8)
	s_waitcnt lgkmcnt(0)
	s_barrier
	s_setprio 1
	s_waitcnt lgkmcnt(0)
	s_cmp_eq_u32 s46, 64
	s_cbranch_scc1 .Lp4_padskip_1
	v_mfma_f32_16x16x32_bf16 v[60:63], v[128:131], v[184:187], v[60:63]
	v_mfma_f32_16x16x32_bf16 v[52:55], v[152:155], v[184:187], v[52:55]
	v_mfma_f32_16x16x32_bf16 v[44:47], v[128:131], v[192:195], v[44:47]
	v_mfma_f32_16x16x32_bf16 v[36:39], v[152:155], v[192:195], v[36:39]
	v_mfma_f32_16x16x32_bf16 v[28:31], v[128:131], v[204:207], v[28:31]
	v_mfma_f32_16x16x32_bf16 v[20:23], v[152:155], v[204:207], v[20:23]
	v_mfma_f32_16x16x32_bf16 v[12:15], v[128:131], v[212:215], v[12:15]
	v_mfma_f32_16x16x32_bf16 v[4:7], v[152:155], v[212:215], v[4:7]
	v_mfma_f32_16x16x32_bf16 v[60:63], v[132:135], v[188:191], v[60:63]
	v_mfma_f32_16x16x32_bf16 v[52:55], v[164:167], v[188:191], v[52:55]
	v_mfma_f32_16x16x32_bf16 v[44:47], v[132:135], v[196:199], v[44:47]
	v_mfma_f32_16x16x32_bf16 v[36:39], v[164:167], v[196:199], v[36:39]
	v_mfma_f32_16x16x32_bf16 v[28:31], v[132:135], v[208:211], v[28:31]
	v_mfma_f32_16x16x32_bf16 v[20:23], v[164:167], v[208:211], v[20:23]
	v_mfma_f32_16x16x32_bf16 v[12:15], v[132:135], v[216:219], v[12:15]
	v_mfma_f32_16x16x32_bf16 v[4:7], v[164:167], v[216:219], v[4:7]
	v_mfma_f32_16x16x32_bf16 v[56:59], v[168:171], v[184:187], v[56:59]
	v_mfma_f32_16x16x32_bf16 v[48:51], v[176:179], v[184:187], v[48:51]
	v_mfma_f32_16x16x32_bf16 v[40:43], v[168:171], v[192:195], v[40:43]
	v_mfma_f32_16x16x32_bf16 v[32:35], v[176:179], v[192:195], v[32:35]
	v_mfma_f32_16x16x32_bf16 v[24:27], v[168:171], v[204:207], v[24:27]
	v_mfma_f32_16x16x32_bf16 v[16:19], v[176:179], v[204:207], v[16:19]
	v_mfma_f32_16x16x32_bf16 v[8:11], v[168:171], v[212:215], v[8:11]
	v_mfma_f32_16x16x32_bf16 v[0:3], v[176:179], v[212:215], v[0:3]
	v_mfma_f32_16x16x32_bf16 v[56:59], v[172:175], v[188:191], v[56:59]
	v_mfma_f32_16x16x32_bf16 v[48:51], v[180:183], v[188:191], v[48:51]
	v_mfma_f32_16x16x32_bf16 v[40:43], v[172:175], v[196:199], v[40:43]
	v_mfma_f32_16x16x32_bf16 v[32:35], v[180:183], v[196:199], v[32:35]
	v_mfma_f32_16x16x32_bf16 v[24:27], v[172:175], v[208:211], v[24:27]
	v_mfma_f32_16x16x32_bf16 v[16:19], v[180:183], v[208:211], v[16:19]
	v_mfma_f32_16x16x32_bf16 v[8:11], v[172:175], v[216:219], v[8:11]
	v_mfma_f32_16x16x32_bf16 v[0:3], v[180:183], v[216:219], v[0:3]
; #define PG8_STAGE(bufoff, gbase, voff) do { _Pragma("unroll") for (int _i = 0; _i < 2; ++_i) \
;         __builtin_amdgcn_global_load_lds((const unsigned*)((const char*)(gbase) + (voff)[_i]), (LAS unsigned*)(lds + (bufoff) + ldsw + _i * 8192), 16, 0, 0); } while (0)
; #define PG8_LDA(dst, b, h) do { _Pragma("unroll") for (int m = 0; m < 4; ++m) _Pragma("unroll") for (int k = 0; k < 2; ++k) dst[m][k] = *(const LAS bf16x8*)(lds + PG8_SA(b, h) + aoff + m * 2048 + k * 1024); } while (0)
; #define PG8_LDB(dst, b, h) do { _Pragma("unroll") for (int n = 0; n < 2; ++n) _Pragma("unroll") for (int k = 0; k < 2; ++k) dst[n][k] = *(const LAS bf16x8*)(lds + PG8_SB(b, h) + boff + n * 2048 + k * 1024); } while (0)
; #define PG8_MMA(ai, bj, At, Bt) do { __builtin_amdgcn_s_setprio(1); _Pragma("unroll") for (int m = 0; m < 4; ++m) _Pragma("unroll") for (int n = 0; n < 2; ++n) _Pragma("unroll") for (int k = 0; k < 2; ++k) \
;         acc[ai][bj][m][n] = __builtin_amdgcn_mfma_f32_16x16x32_bf16(Bt[n][k], At[m][k], acc[ai][bj][m][n], 0, 0, 0); __builtin_amdgcn_s_setprio(0); } while (0)
; #define PG8_WAIT_V(n) asm volatile("s_waitcnt vmcnt(" #n ")" ::: "memory")
; #define PG8_BAR __builtin_amdgcn_s_barrier()
; template <class Epi>
; __device__ __forceinline__ void gemm_phase(LAS unsigned char* lds, const Gemm g, const Sched& S, const Epi& E) {
;     ...
;             PG8_LDB(B0, 0, 0); PG8_LDB(B1, 0, 1); PG8_SCHED; PG8_LDA(At, 0, 0); PG8_STAGE(PG8_SA(1, 1), a1 + hstepA, voffA);
;             PG8_WAIT_V(8); PG8_WAIT_L(0); PG8_BAR; PG8_MMA(0, 0, At, B0); PG8_MMA(0, 1, At, B1); PG8_BAR; PG8_SCHED;
;             PG8_LDA(At, 0, 1); PG8_STAGE(PG8_SB(0, 0), b2, voffB); PG8_STAGE(PG8_SB(0, 1), b2 + hstepB, voffB); PG8_STAGE(PG8_SA(0, 0), a2, voffA);
;             PG8_WAIT_V(8); PG8_WAIT_L(0); PG8_BAR; PG8_MMA(1, 0, At, B0); PG8_MMA(1, 1, At, B1); PG8_BAR; PG8_SCHED;
;             PG8_LDB(B0, 1, 0); PG8_LDB(B1, 1, 1); PG8_SCHED; PG8_LDA(At, 1, 0); PG8_STAGE(PG8_SA(0, 1), a2 + hstepA, voffA);
;             PG8_WAIT_V(8); PG8_WAIT_L(0); PG8_BAR; PG8_MMA(0, 0, At, B0); PG8_MMA(0, 1, At, B1); PG8_BAR; PG8_SCHED;
;             PG8_LDA(At, 1, 1); PG8_STAGE(PG8_SB(1, 0), b3, voffB); PG8_STAGE(PG8_SB(1, 1), b3 + hstepB, voffB); PG8_STAGE(PG8_SA(1, 0), a3, voffA);
;             PG8_WAIT_V(8); PG8_WAIT_L(0); PG8_BAR; PG8_MMA(1, 0, At, B0); PG8_MMA(1, 1, At, B1); PG8_BAR; PG8_SCHED;
.Lp4_padskip_1:
	s_setprio 0
	s_barrier
	s_add_i32 s58, 0, 0x18000
	v_add_u32_e32 v144, s58, v158
	s_add_i32 s59, 0, 0x1c000
	ds_read_b128 v[128:131], v144
	ds_read_b128 v[132:135], v144 offset:1024
	ds_read_b128 v[152:155], v144 offset:2048
	ds_read_b128 v[164:167], v144 offset:3072
	v_add_u32_e32 v144, s59, v158
	ds_read_b128 v[168:171], v144
	ds_read_b128 v[172:175], v144 offset:1024
	ds_read_b128 v[176:179], v144 offset:2048
	ds_read_b128 v[180:183], v144 offset:3072
	s_add_u32 s52, s52, 0x40000
	s_addc_u32 s53, s53, 0
	s_mov_b32 m0, s45
	v_lshl_add_u64 v[226:227], s[52:53], 0, v[136:137]
	ds_read_b128 v[184:187], v162 offset:32768
	ds_read_b128 v[188:191], v162 offset:33792
	ds_read_b128 v[192:195], v162 offset:34816
	ds_read_b128 v[196:199], v162 offset:35840
	ds_read_b128 v[204:207], v162 offset:36864
	ds_read_b128 v[208:211], v162 offset:37888
	ds_read_b128 v[212:215], v162 offset:38912
	ds_read_b128 v[216:219], v162 offset:39936
	global_load_lds_dwordx4 v[226:227], off
	v_lshl_add_u64 v[226:227], s[52:53], 0, v[140:141]
	s_mov_b32 m0, s47
	s_nop 0
	global_load_lds_dwordx4 v[226:227], off
	s_waitcnt vmcnt(8)
	s_waitcnt lgkmcnt(0)
	s_barrier
	s_setprio 1
	s_waitcnt lgkmcnt(0)
	v_mfma_f32_16x16x32_bf16 v[124:127], v[128:131], v[184:187], v[124:127]
	v_mfma_f32_16x16x32_bf16 v[116:119], v[152:155], v[184:187], v[116:119]
	v_mfma_f32_16x16x32_bf16 v[108:111], v[128:131], v[192:195], v[108:111]
	v_mfma_f32_16x16x32_bf16 v[100:103], v[152:155], v[192:195], v[100:103]
	v_mfma_f32_16x16x32_bf16 v[92:95], v[128:131], v[204:207], v[92:95]
	v_mfma_f32_16x16x32_bf16 v[84:87], v[152:155], v[204:207], v[84:87]
	v_mfma_f32_16x16x32_bf16 v[76:79], v[128:131], v[212:215], v[76:79]
	v_mfma_f32_16x16x32_bf16 v[68:71], v[152:155], v[212:215], v[68:71]
	v_mfma_f32_16x16x32_bf16 v[124:127], v[132:135], v[188:191], v[124:127]
	v_mfma_f32_16x16x32_bf16 v[116:119], v[164:167], v[188:191], v[116:119]
	v_mfma_f32_16x16x32_bf16 v[108:111], v[132:135], v[196:199], v[108:111]
	v_mfma_f32_16x16x32_bf16 v[100:103], v[164:167], v[196:199], v[100:103]
	v_mfma_f32_16x16x32_bf16 v[92:95], v[132:135], v[208:211], v[92:95]
	v_mfma_f32_16x16x32_bf16 v[84:87], v[164:167], v[208:211], v[84:87]
	v_mfma_f32_16x16x32_bf16 v[76:79], v[132:135], v[216:219], v[76:79]
	v_mfma_f32_16x16x32_bf16 v[68:71], v[164:167], v[216:219], v[68:71]
	v_mfma_f32_16x16x32_bf16 v[120:123], v[168:171], v[184:187], v[120:123]
	v_mfma_f32_16x16x32_bf16 v[112:115], v[176:179], v[184:187], v[112:115]
	v_mfma_f32_16x16x32_bf16 v[104:107], v[168:171], v[192:195], v[104:107]
	v_mfma_f32_16x16x32_bf16 v[96:99], v[176:179], v[192:195], v[96:99]
	v_mfma_f32_16x16x32_bf16 v[88:91], v[168:171], v[204:207], v[88:91]
	v_mfma_f32_16x16x32_bf16 v[80:83], v[176:179], v[204:207], v[80:83]
	v_mfma_f32_16x16x32_bf16 v[72:75], v[168:171], v[212:215], v[72:75]
	v_mfma_f32_16x16x32_bf16 v[64:67], v[176:179], v[212:215], v[64:67]
	v_mfma_f32_16x16x32_bf16 v[120:123], v[172:175], v[188:191], v[120:123]
	v_mfma_f32_16x16x32_bf16 v[112:115], v[180:183], v[188:191], v[112:115]
	v_mfma_f32_16x16x32_bf16 v[104:107], v[172:175], v[196:199], v[104:107]
	v_mfma_f32_16x16x32_bf16 v[96:99], v[180:183], v[196:199], v[96:99]
	v_mfma_f32_16x16x32_bf16 v[88:91], v[172:175], v[208:211], v[88:91]
	v_mfma_f32_16x16x32_bf16 v[80:83], v[180:183], v[208:211], v[80:83]
	v_mfma_f32_16x16x32_bf16 v[72:75], v[172:175], v[216:219], v[72:75]
	v_mfma_f32_16x16x32_bf16 v[64:67], v[180:183], v[216:219], v[64:67]
	s_setprio 0
	s_barrier
	s_add_i32 s52, s58, s86
	v_lshl_add_u64 v[200:201], v[200:201], 0, s[14:15]
	s_mov_b32 m0, s52
	ds_read_b128 v[184:187], v162 offset:49152
	ds_read_b128 v[188:191], v162 offset:50176
	ds_read_b128 v[192:195], v162 offset:51200
	ds_read_b128 v[196:199], v162 offset:52224
	ds_read_b128 v[204:207], v162 offset:53248
	ds_read_b128 v[208:211], v162 offset:54272
	ds_read_b128 v[212:215], v162 offset:55296
	ds_read_b128 v[216:219], v162 offset:56320
	global_load_lds_dwordx4 v[200:201], off
	s_add_i32 m0, s52, 0x2000
	s_add_u32 s4, s4, 0x40080
	v_lshl_add_u64 v[200:201], v[220:221], 0, s[14:15]
	s_addc_u32 s5, s5, 0
	s_add_i32 s52, s59, s86
	global_load_lds_dwordx4 v[200:201], off
	v_lshl_add_u64 v[200:201], s[4:5], 0, v[138:139]
	s_mov_b32 m0, s52
	s_nop 0
	global_load_lds_dwordx4 v[200:201], off
	v_lshl_add_u64 v[200:201], s[4:5], 0, v[142:143]
	s_add_i32 m0, s52, 0x2000
	s_nop 0
	global_load_lds_dwordx4 v[200:201], off
	v_lshl_add_u64 v[200:201], v[222:223], 0, s[14:15]
	s_mov_b32 m0, s87
	s_nop 0
	global_load_lds_dwordx4 v[200:201], off
	v_lshl_add_u64 v[200:201], v[224:225], 0, s[14:15]
	s_mov_b32 m0, s88
	s_nop 0
	global_load_lds_dwordx4 v[200:201], off
	s_waitcnt vmcnt(8)
	s_waitcnt lgkmcnt(0)
	s_barrier
	s_setprio 1
	s_waitcnt lgkmcnt(0)
	s_cmp_eq_u32 s46, 64
	s_cbranch_scc1 .Lp4_padskip_3
	v_mfma_f32_16x16x32_bf16 v[60:63], v[128:131], v[184:187], v[60:63]
	v_mfma_f32_16x16x32_bf16 v[52:55], v[152:155], v[184:187], v[52:55]
	v_mfma_f32_16x16x32_bf16 v[44:47], v[128:131], v[192:195], v[44:47]
	v_mfma_f32_16x16x32_bf16 v[36:39], v[152:155], v[192:195], v[36:39]
	v_mfma_f32_16x16x32_bf16 v[28:31], v[128:131], v[204:207], v[28:31]
	v_mfma_f32_16x16x32_bf16 v[20:23], v[152:155], v[204:207], v[20:23]
	v_mfma_f32_16x16x32_bf16 v[12:15], v[128:131], v[212:215], v[12:15]
	v_mfma_f32_16x16x32_bf16 v[4:7], v[152:155], v[212:215], v[4:7]
	v_mfma_f32_16x16x32_bf16 v[60:63], v[132:135], v[188:191], v[60:63]
	v_mfma_f32_16x16x32_bf16 v[52:55], v[164:167], v[188:191], v[52:55]
	v_mfma_f32_16x16x32_bf16 v[44:47], v[132:135], v[196:199], v[44:47]
	v_mfma_f32_16x16x32_bf16 v[36:39], v[164:167], v[196:199], v[36:39]
	v_mfma_f32_16x16x32_bf16 v[28:31], v[132:135], v[208:211], v[28:31]
	v_mfma_f32_16x16x32_bf16 v[20:23], v[164:167], v[208:211], v[20:23]
	v_mfma_f32_16x16x32_bf16 v[12:15], v[132:135], v[216:219], v[12:15]
	v_mfma_f32_16x16x32_bf16 v[4:7], v[164:167], v[216:219], v[4:7]
	v_mfma_f32_16x16x32_bf16 v[56:59], v[168:171], v[184:187], v[56:59]
	v_mfma_f32_16x16x32_bf16 v[48:51], v[176:179], v[184:187], v[48:51]
	v_mfma_f32_16x16x32_bf16 v[40:43], v[168:171], v[192:195], v[40:43]
	v_mfma_f32_16x16x32_bf16 v[32:35], v[176:179], v[192:195], v[32:35]
	v_mfma_f32_16x16x32_bf16 v[24:27], v[168:171], v[204:207], v[24:27]
	v_mfma_f32_16x16x32_bf16 v[16:19], v[176:179], v[204:207], v[16:19]
	v_mfma_f32_16x16x32_bf16 v[8:11], v[168:171], v[212:215], v[8:11]
	v_mfma_f32_16x16x32_bf16 v[0:3], v[176:179], v[212:215], v[0:3]
	v_mfma_f32_16x16x32_bf16 v[56:59], v[172:175], v[188:191], v[56:59]
	v_mfma_f32_16x16x32_bf16 v[48:51], v[180:183], v[188:191], v[48:51]
	v_mfma_f32_16x16x32_bf16 v[40:43], v[172:175], v[196:199], v[40:43]
	v_mfma_f32_16x16x32_bf16 v[32:35], v[180:183], v[196:199], v[32:35]
	v_mfma_f32_16x16x32_bf16 v[24:27], v[172:175], v[208:211], v[24:27]
	v_mfma_f32_16x16x32_bf16 v[16:19], v[180:183], v[208:211], v[16:19]
	v_mfma_f32_16x16x32_bf16 v[8:11], v[172:175], v[216:219], v[8:11]
	v_mfma_f32_16x16x32_bf16 v[0:3], v[180:183], v[216:219], v[0:3]
; #define PG8_STAGE(bufoff, gbase, voff) do { _Pragma("unroll") for (int _i = 0; _i < 2; ++_i) \
;         __builtin_amdgcn_global_load_lds((const unsigned*)((const char*)(gbase) + (voff)[_i]), (LAS unsigned*)(lds + (bufoff) + ldsw + _i * 8192), 16, 0, 0); } while (0)
; #define PG8_LDA(dst, b, h) do { _Pragma("unroll") for (int m = 0; m < 4; ++m) _Pragma("unroll") for (int k = 0; k < 2; ++k) dst[m][k] = *(const LAS bf16x8*)(lds + PG8_SA(b, h) + aoff + m * 2048 + k * 1024); } while (0)
; #define PG8_LDB(dst, b, h) do { _Pragma("unroll") for (int n = 0; n < 2; ++n) _Pragma("unroll") for (int k = 0; k < 2; ++k) dst[n][k] = *(const LAS bf16x8*)(lds + PG8_SB(b, h) + boff + n * 2048 + k * 1024); } while (0)
; #define PG8_WAIT_V(n) asm volatile("s_waitcnt vmcnt(" #n ")" ::: "memory")
; template <class Epi>
; __device__ __forceinline__ void gemm_phase(LAS unsigned char* lds, const Gemm g, const Sched& S, const Epi& E) {
;     ...
;         for (int t = 0; t < nt; t += 2) {
;             const bool last = (t == nt - 2);
;             const char* a1 = cA + (size_t)(t + 1) * kstep;
;             const char* a2 = last ? nA : cA + (size_t)(t + 2) * kstep; const char* b2 = last ? nB : cB + (size_t)(t + 2) * kstep;
;             const char* a3 = a2 + kstep; const char* b3 = b2 + kstep;
;             PG8_LDB(B0, 0, 0); PG8_LDB(B1, 0, 1); PG8_SCHED; PG8_LDA(At, 0, 0); PG8_STAGE(PG8_SA(1, 1), a1 + hstepA, voffA);
;             PG8_WAIT_V(8); PG8_WAIT_L(0); PG8_BAR; PG8_MMA(0, 0, At, B0); PG8_MMA(0, 1, At, B1); PG8_BAR; PG8_SCHED;
;             PG8_LDA(At, 0, 1); PG8_STAGE(PG8_SB(0, 0), b2, voffB); PG8_STAGE(PG8_SB(0, 1), b2 + hstepB, voffB); PG8_STAGE(PG8_SA(0, 0), a2, voffA);
;             PG8_WAIT_V(8); PG8_WAIT_L(0); PG8_BAR; PG8_MMA(1, 0, At, B0); PG8_MMA(1, 1, At, B1); PG8_BAR; PG8_SCHED;
;             PG8_LDB(B0, 1, 0); PG8_LDB(B1, 1, 1); PG8_SCHED; PG8_LDA(At, 1, 0); PG8_STAGE(PG8_SA(0, 1), a2 + hstepA, voffA);
;             PG8_WAIT_V(8); PG8_WAIT_L(0); PG8_BAR; PG8_MMA(0, 0, At, B0); PG8_MMA(0, 1, At, B1); PG8_BAR; PG8_SCHED;
;             PG8_LDA(At, 1, 1); PG8_STAGE(PG8_SB(1, 0), b3, voffB); PG8_STAGE(PG8_SB(1, 1), b3 + hstepB, voffB); PG8_STAGE(PG8_SA(1, 0), a3, voffA);
;             PG8_WAIT_V(8); PG8_WAIT_L(0); PG8_BAR; PG8_MMA(1, 0, At, B0); PG8_MMA(1, 1, At, B1); PG8_BAR; PG8_SCHED;
;         }
;         if (wr == 0) PG8_BAR;
.Lp4_padskip_3:
	s_setprio 0
	s_barrier
	s_add_i32 s57, s57, 2
	s_add_u32 s2, s2, 0x100
	s_addc_u32 s3, s3, 0
	s_add_u32 s55, s55, 0x100
	s_addc_u32 s56, s56, 0
	s_cmp_gt_u32 s57, 13
	s_cbranch_scc0 .LBB0_520
	s_and_b64 vcc, exec, s[20:21]
	s_cbranch_vccnz .LBB0_525
	s_sub_i32 s0, s44, 17
	s_cmp_gt_u32 s0, 7
	s_mov_b64 s[2:3], -1
	s_cbranch_scc1 .LBB0_526

; __device__ __forceinline__ u32x2 pack4(f32x4 v) { u32x2 r; r.x = cvt_pk_bf16(v.x, v.y); r.y = cvt_pk_bf16(v.z, v.w); return r; }
; __device__ __forceinline__ float sigm(float x) { return 1.0f / (1.0f + __expf(-x)); }
; template <bool PAIR, class F>
; __device__ __forceinline__ void skinny(const bf16_t* A, int lda, const bf16_t* Bt, int ldb, int K, int tile_lo, int tile_hi, int kmode, int bx, int G, int tid_, LAS unsigned char* lds, F f) {
;     ...
;     for (int un = G - 1 - bx; un < nunits; un += G) {
;         const int rbp = un & 3, cgrp = un >> 2, tile = tile_lo + cgrp / GPT, cgp = (cgrp % GPT) * 4 + cgl;
;         const int n0 = tile * 256 + cgp * 16, row0 = MP + rbp * 32 + fr;
;         const bf16_t* ap = A + (size_t)row0 * lda + (kmode ? 256 * (tile >> 1) : 0) + fq * 8;
;         const bf16_t* bp = Bt + (size_t)(n0 + fr) * ldb + fq * 8;
; template <int ph>
; __device__ __forceinline__ void run_phase(const Args& args, LAS unsigned char* lds, const int G, const int bx, const bool fin = true) {
;     ...
;         skinny<true>(XC, D, LRUT, 256, 256, 0, 8, 1, bx, G, tid, lds, [&](int row, int tile, int cin, f32x4 a, f32x4 b) {
;             const int c = tile * 128 + cin; const f32x4 b0 = *(const f32x4*)(lru_br + c), b1 = *(const f32x4*)(lru_bi + c);
;             *(u32x2*)(GR + (size_t)row * D + c) = pack4((f32x4){sigm(a[0] + b0[0]), sigm(a[1] + b0[1]), sigm(a[2] + b0[2]), sigm(a[3] + b0[3])});
;             *(u32x2*)(GI + (size_t)row * D + c) = pack4((f32x4){sigm(b[0] + b1[0]), sigm(b[1] + b1[1]), sigm(b[2] + b1[2]), sigm(b[3] + b1[3])}); });
.LBB0_926:
	s_mov_b32 s10, s81
	s_cmp_gt_i32 s10, 63
	v_readfirstlane_b32 s0, v158
	s_cbranch_scc1 .LBB0_933
	s_bfe_u32 s1, s0, 0x20006
	s_lshl_b32 s2, s1, 12
	s_ashr_i32 s3, s0, 8
	s_add_i32 s6, s2, 0
	s_lshl_b32 s2, s3, 7
	s_lshl_b32 s11, s1, 4
	v_and_b32_e32 v0, 63, v158
	v_bfe_u32 v2, v158, 4, 2
	s_cmp_eq_u32 s3, 1
	v_lshlrev_b32_e32 v1, 6, v0
	v_lshlrev_b32_e32 v0, 3, v2
	s_cselect_b64 s[4:5], -1, 0
	s_cmpk_lt_u32 s0, 0x100
	v_mov_b32_e32 v25, 0
	v_and_b32_e32 v24, 48, v158
	s_cselect_b64 s[14:15], -1, 0
	s_ashr_i32 s3, s2, 31
	v_lshlrev_b32_e32 v28, 1, v0
	v_cndmask_b32_e64 v0, 0, 1, s[4:5]
	v_and_b32_e32 v36, 15, v158
	v_lshl_add_u64 v[26:27], s[40:41], 0, v[24:25]
	v_lshlrev_b32_e32 v37, 2, v2
	s_lshl_b32 s13, s10, 5
	s_lshl_b32 s40, s33, 5
	v_mov_b32_e32 v29, v25
	s_lshl_b64 s[20:21], s[2:3], 1
	s_mov_b64 s[22:23], 0x8000
	s_mov_b64 s[38:39], 0x10000
	s_mov_b32 s41, 0x8000
	s_mov_b32 s42, 0x10000
	v_cmp_ne_u32_e64 s[2:3], 1, v0
	v_add_u32_e32 v38, s6, v1
	v_mov_b32_e32 v39, 0x2008000
	s_branch .LBB0_929
